# GEMM K-loops: DMA pieces spread 2,2,2,2 over the step's MFMA blocks instead of 4,4,0,0 (re-tested now that operand tiles hit the XCD's L2)
# baseline (speedup 1.0000x reference)
; #define G_STORE(S, bf) { *(uint4*)&s->a[bf][srow][skc] = S##a0; *(uint4*)&s->a[bf][srow + 32][skc] = S##a1; \
;     if (MB == 2) { *(uint4*)&s->a[bf][srow + 64][skc] = S##a2; *(uint4*)&s->a[bf][srow + 96][skc] = S##a3; } \
;     *(uint4*)&s->b[bf][srow][skc] = S##b0; *(uint4*)&s->b[bf][srow + 32][skc] = S##b1; *(uint4*)&s->b[bf][srow + 64][skc] = S##b2; *(uint4*)&s->b[bf][srow + 96][skc] = S##b3; }
; template <int MB, bool PF2 = true>
; DI void gemm_main(const u16* __restrict__ A, int lda, const u16* __restrict__ B, int ldb, int K, f32x16 (&acc)[MB][2], GemmLds* s, int tid) {
;     ...
;   for (int kt = 0; kt < KT; kt += 2) {
;     { const int k2 = min((kt + 2) * 64, klast); G_LOAD(q, k2); }
;     __builtin_amdgcn_sched_barrier(0);
;     G_COMPUTE(0);
;     G_STORE(p, 1);
;     __syncthreads();
;     { const int k3 = min((kt + 3) * 64, klast); G_LOAD(p, k3); }
;     __builtin_amdgcn_sched_barrier(0);
;     G_COMPUTE(1);
;     G_STORE(q, 0);
;     __syncthreads();
;   }
; DI void phase_inproj(const Params& p, int l, char* smem, int tid) {
;     ...
;     f32x16 acc[2][2]; zero_acc<2>(acc);
;     gemm_main<2>(p.xn + (size_t)m0 * 1024, 1024, Wt + (size_t)n0 * 1024, 1024, 1024, acc, s, tid);
.Lip_again:
	v_mov_b32_e32 v2, 0
	v_mov_b32_e32 v3, 0
	v_mov_b32_e32 v4, 0
	v_mov_b32_e32 v5, 0
	v_mov_b32_e32 v6, 0
	v_mov_b32_e32 v7, 0
	v_mov_b32_e32 v8, 0
	v_mov_b32_e32 v9, 0
	v_mov_b32_e32 v10, 0
	v_mov_b32_e32 v11, 0
	v_mov_b32_e32 v12, 0
	v_mov_b32_e32 v13, 0
	v_mov_b32_e32 v14, 0
	v_mov_b32_e32 v15, 0
	v_mov_b32_e32 v16, 0
	v_mov_b32_e32 v17, 0
	v_mov_b32_e32 v18, 0
	v_mov_b32_e32 v19, 0
	v_mov_b32_e32 v20, 0
	v_mov_b32_e32 v21, 0
	v_mov_b32_e32 v22, 0
	v_mov_b32_e32 v23, 0
	v_mov_b32_e32 v24, 0
	v_mov_b32_e32 v25, 0
	v_mov_b32_e32 v26, 0
	v_mov_b32_e32 v27, 0
	v_mov_b32_e32 v28, 0
	v_mov_b32_e32 v29, 0
	v_mov_b32_e32 v30, 0
	v_mov_b32_e32 v31, 0
	v_mov_b32_e32 v32, 0
	v_mov_b32_e32 v33, 0
	v_mov_b32_e32 v34, 0
	v_mov_b32_e32 v35, 0
	v_mov_b32_e32 v36, 0
	v_mov_b32_e32 v37, 0
	v_mov_b32_e32 v38, 0
	v_mov_b32_e32 v39, 0
	v_mov_b32_e32 v40, 0
	v_mov_b32_e32 v41, 0
	v_mov_b32_e32 v42, 0
	v_mov_b32_e32 v43, 0
	v_mov_b32_e32 v44, 0
	v_mov_b32_e32 v45, 0
	v_mov_b32_e32 v46, 0
	v_mov_b32_e32 v47, 0
	v_mov_b32_e32 v48, 0
	v_mov_b32_e32 v49, 0
	v_mov_b32_e32 v50, 0
	v_mov_b32_e32 v51, 0
	v_mov_b32_e32 v52, 0
	v_mov_b32_e32 v53, 0
	v_mov_b32_e32 v54, 0
	v_mov_b32_e32 v55, 0
	v_mov_b32_e32 v56, 0
	v_mov_b32_e32 v57, 0
	v_mov_b32_e32 v58, 0
	v_mov_b32_e32 v59, 0
	v_mov_b32_e32 v60, 0
	v_mov_b32_e32 v61, 0
	v_mov_b32_e32 v62, 0
	v_mov_b32_e32 v63, 0
	v_mov_b32_e32 v64, 0
	v_mov_b32_e32 v65, 0
	s_waitcnt vmcnt(0) lgkmcnt(0)
	s_barrier
	ds_read_b128 v[66:69], v102 offset:0
	ds_read_b128 v[74:77], v106 offset:0
	ds_read_b128 v[70:73], v102 offset:4096
	ds_read_b128 v[78:81], v106 offset:4096
	s_add_u32 m0, s10, 0x8000
	s_nop 0
	global_load_lds_dwordx4 v98, s[4:5]
	s_add_u32 m0, s10, 0x8400
	s_nop 0
	global_load_lds_dwordx4 v99, s[4:5]
	s_mov_b32 s11, 7
.Lip_loop:
	ds_read_b128 v[82:85], v103 offset:0
	ds_read_b128 v[90:93], v107 offset:0
	ds_read_b128 v[86:89], v103 offset:4096
	ds_read_b128 v[94:97], v107 offset:4096
	s_waitcnt lgkmcnt(4)
	s_add_u32 m0, s10, 0x8800
	v_mfma_f32_32x32x16_bf16 v[2:17], v[74:77], v[66:69], v[2:17]
	global_load_lds_dwordx4 v100, s[4:5]
	s_add_u32 m0, s10, 0x8c00
	v_mfma_f32_32x32x16_bf16 v[18:33], v[78:81], v[66:69], v[18:33]
	global_load_lds_dwordx4 v101, s[4:5]
	s_add_u32 s4, s4, 128
	s_addc_u32 s5, s5, 0
	v_mfma_f32_32x32x16_bf16 v[34:49], v[74:77], v[70:73], v[34:49]
	v_mfma_f32_32x32x16_bf16 v[50:65], v[78:81], v[70:73], v[50:65]
	ds_read_b128 v[66:69], v104 offset:0
	ds_read_b128 v[74:77], v108 offset:0
	ds_read_b128 v[70:73], v104 offset:4096
	ds_read_b128 v[78:81], v108 offset:4096
	s_waitcnt lgkmcnt(4)
	s_add_u32 m0, s10, 0xc000
	v_mfma_f32_32x32x16_bf16 v[2:17], v[90:93], v[82:85], v[2:17]
	global_load_lds_dwordx4 v98, s[8:9]
	s_add_u32 m0, s10, 0xc400
	v_mfma_f32_32x32x16_bf16 v[18:33], v[94:97], v[82:85], v[18:33]
	global_load_lds_dwordx4 v99, s[8:9]
	v_mfma_f32_32x32x16_bf16 v[34:49], v[90:93], v[86:89], v[34:49]
	v_mfma_f32_32x32x16_bf16 v[50:65], v[94:97], v[86:89], v[50:65]
	ds_read_b128 v[82:85], v105 offset:0
	ds_read_b128 v[90:93], v109 offset:0
	ds_read_b128 v[86:89], v105 offset:4096
	ds_read_b128 v[94:97], v109 offset:4096
	s_waitcnt lgkmcnt(4)
	s_add_u32 m0, s10, 0xc800
	v_mfma_f32_32x32x16_bf16 v[2:17], v[74:77], v[66:69], v[2:17]
	global_load_lds_dwordx4 v100, s[8:9]
	s_add_u32 m0, s10, 0xcc00
	v_mfma_f32_32x32x16_bf16 v[18:33], v[78:81], v[66:69], v[18:33]
	global_load_lds_dwordx4 v101, s[8:9]
	s_add_u32 s8, s8, 128
	s_addc_u32 s9, s9, 0
	v_mfma_f32_32x32x16_bf16 v[34:49], v[74:77], v[70:73], v[34:49]
	v_mfma_f32_32x32x16_bf16 v[50:65], v[78:81], v[70:73], v[50:65]
	s_waitcnt vmcnt(0) lgkmcnt(0)
	s_barrier
	ds_read_b128 v[66:69], v102 offset:32768
	ds_read_b128 v[74:77], v106 offset:32768
	ds_read_b128 v[70:73], v102 offset:36864
	ds_read_b128 v[78:81], v106 offset:36864
	s_cmp_eq_u32 s11, 0
	s_cbranch_scc1 .Lip_hold0
	s_add_u32 m0, s10, 0x0
	v_mfma_f32_32x32x16_bf16 v[2:17], v[90:93], v[82:85], v[2:17]
	global_load_lds_dwordx4 v98, s[4:5]
	s_add_u32 m0, s10, 0x400
	v_mfma_f32_32x32x16_bf16 v[18:33], v[94:97], v[82:85], v[18:33]
	global_load_lds_dwordx4 v99, s[4:5]
	v_mfma_f32_32x32x16_bf16 v[34:49], v[90:93], v[86:89], v[34:49]
	v_mfma_f32_32x32x16_bf16 v[50:65], v[94:97], v[86:89], v[50:65]
	s_branch .Lip_held0

; #define G_STORE(S, bf) { *(uint4*)&s->a[bf][srow][skc] = S##a0; *(uint4*)&s->a[bf][srow + 32][skc] = S##a1; \
;     if (MB == 2) { *(uint4*)&s->a[bf][srow + 64][skc] = S##a2; *(uint4*)&s->a[bf][srow + 96][skc] = S##a3; } \
;     *(uint4*)&s->b[bf][srow][skc] = S##b0; *(uint4*)&s->b[bf][srow + 32][skc] = S##b1; *(uint4*)&s->b[bf][srow + 64][skc] = S##b2; *(uint4*)&s->b[bf][srow + 96][skc] = S##b3; }
; template <int MB, bool PF2 = true>
; DI void gemm_main(const u16* __restrict__ A, int lda, const u16* __restrict__ B, int ldb, int K, f32x16 (&acc)[MB][2], GemmLds* s, int tid) {
;     ...
;   for (int kt = 0; kt < KT; kt += 2) {
;     { const int k2 = min((kt + 2) * 64, klast); G_LOAD(q, k2); }
;     __builtin_amdgcn_sched_barrier(0);
;     G_COMPUTE(0);
;     G_STORE(p, 1);
;     __syncthreads();
;     { const int k3 = min((kt + 3) * 64, klast); G_LOAD(p, k3); }
;     __builtin_amdgcn_sched_barrier(0);
;     G_COMPUTE(1);
;     G_STORE(q, 0);
;     __syncthreads();
;   }
.Lip_held0:
	s_cmp_eq_u32 s11, 0
	s_cbranch_scc1 .Lip_last
	ds_read_b128 v[82:85], v103 offset:32768
	ds_read_b128 v[90:93], v107 offset:32768
	ds_read_b128 v[86:89], v103 offset:36864
	ds_read_b128 v[94:97], v107 offset:36864
	s_waitcnt lgkmcnt(4)
	s_add_u32 m0, s10, 0x800
	v_mfma_f32_32x32x16_bf16 v[2:17], v[74:77], v[66:69], v[2:17]
	global_load_lds_dwordx4 v100, s[4:5]
	s_add_u32 m0, s10, 0xc00
	v_mfma_f32_32x32x16_bf16 v[18:33], v[78:81], v[66:69], v[18:33]
	global_load_lds_dwordx4 v101, s[4:5]
	s_add_u32 s4, s4, 128
	s_addc_u32 s5, s5, 0
	v_mfma_f32_32x32x16_bf16 v[34:49], v[74:77], v[70:73], v[34:49]
	v_mfma_f32_32x32x16_bf16 v[50:65], v[78:81], v[70:73], v[50:65]
	ds_read_b128 v[66:69], v104 offset:32768
	ds_read_b128 v[74:77], v108 offset:32768
	ds_read_b128 v[70:73], v104 offset:36864
	ds_read_b128 v[78:81], v108 offset:36864
	s_waitcnt lgkmcnt(4)
	s_add_u32 m0, s10, 0x4000
	v_mfma_f32_32x32x16_bf16 v[2:17], v[90:93], v[82:85], v[2:17]
	global_load_lds_dwordx4 v98, s[8:9]
	s_add_u32 m0, s10, 0x4400
	v_mfma_f32_32x32x16_bf16 v[18:33], v[94:97], v[82:85], v[18:33]
	global_load_lds_dwordx4 v99, s[8:9]
	v_mfma_f32_32x32x16_bf16 v[34:49], v[90:93], v[86:89], v[34:49]
	v_mfma_f32_32x32x16_bf16 v[50:65], v[94:97], v[86:89], v[50:65]
	ds_read_b128 v[82:85], v105 offset:32768
	ds_read_b128 v[90:93], v109 offset:32768
	ds_read_b128 v[86:89], v105 offset:36864
	ds_read_b128 v[94:97], v109 offset:36864
	s_waitcnt lgkmcnt(4)
	s_add_u32 m0, s10, 0x4800
	v_mfma_f32_32x32x16_bf16 v[2:17], v[74:77], v[66:69], v[2:17]
	global_load_lds_dwordx4 v100, s[8:9]
	s_add_u32 m0, s10, 0x4c00
	v_mfma_f32_32x32x16_bf16 v[18:33], v[78:81], v[66:69], v[18:33]
	global_load_lds_dwordx4 v101, s[8:9]
	s_add_u32 s8, s8, 128
	s_addc_u32 s9, s9, 0
	v_mfma_f32_32x32x16_bf16 v[34:49], v[74:77], v[70:73], v[34:49]
	v_mfma_f32_32x32x16_bf16 v[50:65], v[78:81], v[70:73], v[50:65]
	s_waitcnt vmcnt(0) lgkmcnt(0)
	s_barrier
	ds_read_b128 v[66:69], v102 offset:0
	ds_read_b128 v[74:77], v106 offset:0
	ds_read_b128 v[70:73], v102 offset:4096
	ds_read_b128 v[78:81], v106 offset:4096
	s_add_u32 m0, s10, 0x8000
	v_mfma_f32_32x32x16_bf16 v[2:17], v[90:93], v[82:85], v[2:17]
	global_load_lds_dwordx4 v98, s[4:5]
	s_add_u32 m0, s10, 0x8400
	v_mfma_f32_32x32x16_bf16 v[18:33], v[94:97], v[82:85], v[18:33]
	global_load_lds_dwordx4 v99, s[4:5]
	v_mfma_f32_32x32x16_bf16 v[34:49], v[90:93], v[86:89], v[34:49]
	v_mfma_f32_32x32x16_bf16 v[50:65], v[94:97], v[86:89], v[50:65]
	s_sub_u32 s11, s11, 1
	s_branch .Lip_loop

; #define G_STORE(S, bf) { *(uint4*)&s->a[bf][srow][skc] = S##a0; *(uint4*)&s->a[bf][srow + 32][skc] = S##a1; \
;     if (MB == 2) { *(uint4*)&s->a[bf][srow + 64][skc] = S##a2; *(uint4*)&s->a[bf][srow + 96][skc] = S##a3; } \
;     *(uint4*)&s->b[bf][srow][skc] = S##b0; *(uint4*)&s->b[bf][srow + 32][skc] = S##b1; *(uint4*)&s->b[bf][srow + 64][skc] = S##b2; *(uint4*)&s->b[bf][srow + 96][skc] = S##b3; }
; template <int MB, bool PF2 = true>
; DI void gemm_main(const u16* __restrict__ A, int lda, const u16* __restrict__ B, int ldb, int K, f32x16 (&acc)[MB][2], GemmLds* s, int tid) {
;     ...
;   for (int kt = 0; kt < KT; kt += 2) {
;     { const int k2 = min((kt + 2) * 64, klast); G_LOAD(q, k2); }
;     __builtin_amdgcn_sched_barrier(0);
;     G_COMPUTE(0);
;     G_STORE(p, 1);
;     __syncthreads();
;     { const int k3 = min((kt + 3) * 64, klast); G_LOAD(p, k3); }
;     __builtin_amdgcn_sched_barrier(0);
;     G_COMPUTE(1);
;     G_STORE(q, 0);
;     __syncthreads();
;   }
; DI void phase_merge(const Params& p, int l, char* smem, int tid) {
;     ...
;     f32x16 accT[1][2]; zero_acc<1>(accT);
; #pragma unroll 1
;     for (int i = 0; i < 4; i++) {
;       if ((ZERO_MASK >> i) & 1) continue;
;       unsigned sg[2][8];
;       {
;         f32x16 m[1][2]; zero_acc<1>(m);
;         gemm_main<1>(p.xn + (size_t)m0 * 1024, 1024, p.WtM + (size_t)l * 4096 * 1024 + ((size_t)i * 1024 + n0) * 1024, 1024, 1024, m, s, tid);
.Lmg_seg:
	v_mov_b32_e32 v66, 0
	v_mov_b32_e32 v67, 0
	v_mov_b32_e32 v68, 0
	v_mov_b32_e32 v69, 0
	v_mov_b32_e32 v70, 0
	v_mov_b32_e32 v71, 0
	v_mov_b32_e32 v72, 0
	v_mov_b32_e32 v73, 0
	v_mov_b32_e32 v74, 0
	v_mov_b32_e32 v75, 0
	v_mov_b32_e32 v76, 0
	v_mov_b32_e32 v77, 0
	v_mov_b32_e32 v78, 0
	v_mov_b32_e32 v79, 0
	v_mov_b32_e32 v80, 0
	v_mov_b32_e32 v81, 0
	v_mov_b32_e32 v82, 0
	v_mov_b32_e32 v83, 0
	v_mov_b32_e32 v84, 0
	v_mov_b32_e32 v85, 0
	v_mov_b32_e32 v86, 0
	v_mov_b32_e32 v87, 0
	v_mov_b32_e32 v88, 0
	v_mov_b32_e32 v89, 0
	v_mov_b32_e32 v90, 0
	v_mov_b32_e32 v91, 0
	v_mov_b32_e32 v92, 0
	v_mov_b32_e32 v93, 0
	v_mov_b32_e32 v94, 0
	v_mov_b32_e32 v95, 0
	v_mov_b32_e32 v96, 0
	v_mov_b32_e32 v97, 0
	v_mov_b32_e32 v98, 0
	v_mov_b32_e32 v99, 0
	v_mov_b32_e32 v100, 0
	v_mov_b32_e32 v101, 0
	v_mov_b32_e32 v102, 0
	v_mov_b32_e32 v103, 0
	v_mov_b32_e32 v104, 0
	v_mov_b32_e32 v105, 0
	v_mov_b32_e32 v106, 0
	v_mov_b32_e32 v107, 0
	v_mov_b32_e32 v108, 0
	v_mov_b32_e32 v109, 0
	v_mov_b32_e32 v110, 0
	v_mov_b32_e32 v111, 0
	v_mov_b32_e32 v112, 0
	v_mov_b32_e32 v113, 0
	v_mov_b32_e32 v114, 0
	v_mov_b32_e32 v115, 0
	v_mov_b32_e32 v116, 0
	v_mov_b32_e32 v117, 0
	v_mov_b32_e32 v118, 0
	v_mov_b32_e32 v119, 0
	v_mov_b32_e32 v120, 0
	v_mov_b32_e32 v121, 0
	v_mov_b32_e32 v122, 0
	v_mov_b32_e32 v123, 0
	v_mov_b32_e32 v124, 0
	v_mov_b32_e32 v125, 0
	v_mov_b32_e32 v126, 0
	v_mov_b32_e32 v127, 0
	v_mov_b32_e32 v128, 0
	v_mov_b32_e32 v129, 0
	s_waitcnt vmcnt(0) lgkmcnt(0)
	s_barrier
	ds_read_b128 v[224:227], v138 offset:0
	ds_read_b128 v[232:235], v142 offset:0
	ds_read_b128 v[228:231], v138 offset:4096
	ds_read_b128 v[236:239], v142 offset:4096
	s_add_u32 m0, s10, 0x8000
	s_nop 0
	global_load_lds_dwordx4 v200, s[4:5]
	s_add_u32 m0, s10, 0x8400
	s_nop 0
	global_load_lds_dwordx4 v201, s[4:5]
	s_mov_b32 s11, 7
.Lmgm_loop:
	ds_read_b128 v[240:243], v139 offset:0
	ds_read_b128 v[192:195], v143 offset:0
	ds_read_b128 v[188:191], v139 offset:4096
	ds_read_b128 v[196:199], v143 offset:4096
	s_waitcnt lgkmcnt(4)
	s_add_u32 m0, s10, 0x8800
	v_mfma_f32_32x32x16_bf16 v[66:81], v[232:235], v[224:227], v[66:81]
	global_load_lds_dwordx4 v202, s[4:5]
	s_add_u32 m0, s10, 0x8c00
	v_mfma_f32_32x32x16_bf16 v[82:97], v[236:239], v[224:227], v[82:97]
	global_load_lds_dwordx4 v203, s[4:5]
	s_add_u32 s4, s4, 128
	s_addc_u32 s5, s5, 0
	v_mfma_f32_32x32x16_bf16 v[98:113], v[232:235], v[228:231], v[98:113]
	v_mfma_f32_32x32x16_bf16 v[114:129], v[236:239], v[228:231], v[114:129]
	ds_read_b128 v[224:227], v140 offset:0
	ds_read_b128 v[232:235], v144 offset:0
	ds_read_b128 v[228:231], v140 offset:4096
	ds_read_b128 v[236:239], v144 offset:4096
	s_waitcnt lgkmcnt(4)
	s_add_u32 m0, s10, 0xc000
	v_mfma_f32_32x32x16_bf16 v[66:81], v[192:195], v[240:243], v[66:81]
	global_load_lds_dwordx4 v200, s[8:9]
	s_add_u32 m0, s10, 0xc400
	v_mfma_f32_32x32x16_bf16 v[82:97], v[196:199], v[240:243], v[82:97]
	global_load_lds_dwordx4 v201, s[8:9]
	v_mfma_f32_32x32x16_bf16 v[98:113], v[192:195], v[188:191], v[98:113]
	v_mfma_f32_32x32x16_bf16 v[114:129], v[196:199], v[188:191], v[114:129]
	ds_read_b128 v[240:243], v141 offset:0
	ds_read_b128 v[192:195], v145 offset:0
	ds_read_b128 v[188:191], v141 offset:4096
	ds_read_b128 v[196:199], v145 offset:4096
	s_waitcnt lgkmcnt(4)
	s_add_u32 m0, s10, 0xc800
	v_mfma_f32_32x32x16_bf16 v[66:81], v[232:235], v[224:227], v[66:81]
	global_load_lds_dwordx4 v202, s[8:9]
	s_add_u32 m0, s10, 0xcc00
	v_mfma_f32_32x32x16_bf16 v[82:97], v[236:239], v[224:227], v[82:97]
	global_load_lds_dwordx4 v203, s[8:9]
	s_add_u32 s8, s8, 128
	s_addc_u32 s9, s9, 0
	v_mfma_f32_32x32x16_bf16 v[98:113], v[232:235], v[228:231], v[98:113]
	v_mfma_f32_32x32x16_bf16 v[114:129], v[236:239], v[228:231], v[114:129]
	s_waitcnt vmcnt(0) lgkmcnt(0)
	s_barrier
	ds_read_b128 v[224:227], v138 offset:32768
	ds_read_b128 v[232:235], v142 offset:32768
	ds_read_b128 v[228:231], v138 offset:36864
	ds_read_b128 v[236:239], v142 offset:36864
	s_cmp_eq_u32 s11, 0
	s_cbranch_scc1 .Lmgm_hold0
	s_add_u32 m0, s10, 0x0
	v_mfma_f32_32x32x16_bf16 v[66:81], v[192:195], v[240:243], v[66:81]
	global_load_lds_dwordx4 v200, s[4:5]
	s_add_u32 m0, s10, 0x400
	v_mfma_f32_32x32x16_bf16 v[82:97], v[196:199], v[240:243], v[82:97]
	global_load_lds_dwordx4 v201, s[4:5]
	v_mfma_f32_32x32x16_bf16 v[98:113], v[192:195], v[188:191], v[98:113]
	v_mfma_f32_32x32x16_bf16 v[114:129], v[196:199], v[188:191], v[114:129]
	s_branch .Lmgm_held0

; #define G_STORE(S, bf) { *(uint4*)&s->a[bf][srow][skc] = S##a0; *(uint4*)&s->a[bf][srow + 32][skc] = S##a1; \
;     if (MB == 2) { *(uint4*)&s->a[bf][srow + 64][skc] = S##a2; *(uint4*)&s->a[bf][srow + 96][skc] = S##a3; } \
;     *(uint4*)&s->b[bf][srow][skc] = S##b0; *(uint4*)&s->b[bf][srow + 32][skc] = S##b1; *(uint4*)&s->b[bf][srow + 64][skc] = S##b2; *(uint4*)&s->b[bf][srow + 96][skc] = S##b3; }
; template <int MB, bool PF2 = true>
; DI void gemm_main(const u16* __restrict__ A, int lda, const u16* __restrict__ B, int ldb, int K, f32x16 (&acc)[MB][2], GemmLds* s, int tid) {
;     ...
;   for (int kt = 0; kt < KT; kt += 2) {
;     { const int k2 = min((kt + 2) * 64, klast); G_LOAD(q, k2); }
;     __builtin_amdgcn_sched_barrier(0);
;     G_COMPUTE(0);
;     G_STORE(p, 1);
;     __syncthreads();
;     { const int k3 = min((kt + 3) * 64, klast); G_LOAD(p, k3); }
;     __builtin_amdgcn_sched_barrier(0);
;     G_COMPUTE(1);
;     G_STORE(q, 0);
;     __syncthreads();
;   }
.Lmgm_held0:
	s_cmp_eq_u32 s11, 0
	s_cbranch_scc1 .Lmgm_last
	ds_read_b128 v[240:243], v139 offset:32768
	ds_read_b128 v[192:195], v143 offset:32768
	ds_read_b128 v[188:191], v139 offset:36864
	ds_read_b128 v[196:199], v143 offset:36864
	s_waitcnt lgkmcnt(4)
	s_add_u32 m0, s10, 0x800
	v_mfma_f32_32x32x16_bf16 v[66:81], v[232:235], v[224:227], v[66:81]
	global_load_lds_dwordx4 v202, s[4:5]
	s_add_u32 m0, s10, 0xc00
	v_mfma_f32_32x32x16_bf16 v[82:97], v[236:239], v[224:227], v[82:97]
	global_load_lds_dwordx4 v203, s[4:5]
	s_add_u32 s4, s4, 128
	s_addc_u32 s5, s5, 0
	v_mfma_f32_32x32x16_bf16 v[98:113], v[232:235], v[228:231], v[98:113]
	v_mfma_f32_32x32x16_bf16 v[114:129], v[236:239], v[228:231], v[114:129]
	ds_read_b128 v[224:227], v140 offset:32768
	ds_read_b128 v[232:235], v144 offset:32768
	ds_read_b128 v[228:231], v140 offset:36864
	ds_read_b128 v[236:239], v144 offset:36864
	s_waitcnt lgkmcnt(4)
	s_add_u32 m0, s10, 0x4000
	v_mfma_f32_32x32x16_bf16 v[66:81], v[192:195], v[240:243], v[66:81]
	global_load_lds_dwordx4 v200, s[8:9]
	s_add_u32 m0, s10, 0x4400
	v_mfma_f32_32x32x16_bf16 v[82:97], v[196:199], v[240:243], v[82:97]
	global_load_lds_dwordx4 v201, s[8:9]
	v_mfma_f32_32x32x16_bf16 v[98:113], v[192:195], v[188:191], v[98:113]
	v_mfma_f32_32x32x16_bf16 v[114:129], v[196:199], v[188:191], v[114:129]
	ds_read_b128 v[240:243], v141 offset:32768
	ds_read_b128 v[192:195], v145 offset:32768
	ds_read_b128 v[188:191], v141 offset:36864
	ds_read_b128 v[196:199], v145 offset:36864
	s_waitcnt lgkmcnt(4)
	s_add_u32 m0, s10, 0x4800
	v_mfma_f32_32x32x16_bf16 v[66:81], v[232:235], v[224:227], v[66:81]
	global_load_lds_dwordx4 v202, s[8:9]
	s_add_u32 m0, s10, 0x4c00
	v_mfma_f32_32x32x16_bf16 v[82:97], v[236:239], v[224:227], v[82:97]
	global_load_lds_dwordx4 v203, s[8:9]
	s_add_u32 s8, s8, 128
	s_addc_u32 s9, s9, 0
	v_mfma_f32_32x32x16_bf16 v[98:113], v[232:235], v[228:231], v[98:113]
	v_mfma_f32_32x32x16_bf16 v[114:129], v[236:239], v[228:231], v[114:129]
	s_waitcnt vmcnt(0) lgkmcnt(0)
	s_barrier
	ds_read_b128 v[224:227], v138 offset:0
	ds_read_b128 v[232:235], v142 offset:0
	ds_read_b128 v[228:231], v138 offset:4096
	ds_read_b128 v[236:239], v142 offset:4096
	s_add_u32 m0, s10, 0x8000
	v_mfma_f32_32x32x16_bf16 v[66:81], v[192:195], v[240:243], v[66:81]
	global_load_lds_dwordx4 v200, s[4:5]
	s_add_u32 m0, s10, 0x8400
	v_mfma_f32_32x32x16_bf16 v[82:97], v[196:199], v[240:243], v[82:97]
	global_load_lds_dwordx4 v201, s[4:5]
	v_mfma_f32_32x32x16_bf16 v[98:113], v[192:195], v[188:191], v[98:113]
	v_mfma_f32_32x32x16_bf16 v[114:129], v[196:199], v[188:191], v[114:129]
	s_sub_u32 s11, s11, 1
	s_branch .Lmgm_loop

; DI unsigned pack2(float a, float b) { f32v2 v = {a, b}; return __builtin_bit_cast(unsigned, __builtin_convertvector(v, bf16v2)); }
; DI float sigm_fast(float x) { return __builtin_amdgcn_rcpf(1.f + __expf(-x)); }
; DI void phase_merge(const Params& p, int l, char* smem, int tid) {
;     ...
; #pragma unroll
;         for (int b2 = 0; b2 < 2; b2++)
; #pragma unroll
;           for (int e = 0; e < 8; e++) sg[b2][e] = pack2(sigm_fast(m[0][b2][2 * e]), sigm_fast(m[0][b2][2 * e + 1]));
.Lmgm_kdone:
	s_nop 7
	s_nop 7
	v_mul_f32_e32 v66, 0xbfb8aa3b, v66
	v_mul_f32_e32 v67, 0xbfb8aa3b, v67
	v_mul_f32_e32 v68, 0xbfb8aa3b, v68
	v_mul_f32_e32 v69, 0xbfb8aa3b, v69
	v_mul_f32_e32 v70, 0xbfb8aa3b, v70
	v_mul_f32_e32 v71, 0xbfb8aa3b, v71
	v_mul_f32_e32 v72, 0xbfb8aa3b, v72
	v_mul_f32_e32 v73, 0xbfb8aa3b, v73
	v_exp_f32_e32 v66, v66
	v_exp_f32_e32 v67, v67
	v_exp_f32_e32 v68, v68
	v_exp_f32_e32 v69, v69
	v_exp_f32_e32 v70, v70
	v_exp_f32_e32 v71, v71
	v_exp_f32_e32 v72, v72
	v_exp_f32_e32 v73, v73
	v_add_f32_e32 v66, 1.0, v66
	v_add_f32_e32 v67, 1.0, v67
	v_add_f32_e32 v68, 1.0, v68
	v_add_f32_e32 v69, 1.0, v69
	v_add_f32_e32 v70, 1.0, v70
	v_add_f32_e32 v71, 1.0, v71
	v_add_f32_e32 v72, 1.0, v72
	v_add_f32_e32 v73, 1.0, v73
	v_rcp_f32_e32 v66, v66
	v_rcp_f32_e32 v67, v67
	v_rcp_f32_e32 v68, v68
	v_rcp_f32_e32 v69, v69
	v_rcp_f32_e32 v70, v70
	v_rcp_f32_e32 v71, v71
	v_rcp_f32_e32 v72, v72
	v_rcp_f32_e32 v73, v73
	s_nop 0
	v_cvt_pk_bf16_f32 v156, v66, v67
	v_cvt_pk_bf16_f32 v157, v68, v69
	v_cvt_pk_bf16_f32 v158, v70, v71
	v_cvt_pk_bf16_f32 v159, v72, v73
	v_mul_f32_e32 v74, 0xbfb8aa3b, v74
	v_mul_f32_e32 v75, 0xbfb8aa3b, v75
	v_mul_f32_e32 v76, 0xbfb8aa3b, v76
	v_mul_f32_e32 v77, 0xbfb8aa3b, v77
	v_mul_f32_e32 v78, 0xbfb8aa3b, v78
	v_mul_f32_e32 v79, 0xbfb8aa3b, v79
	v_mul_f32_e32 v80, 0xbfb8aa3b, v80
	v_mul_f32_e32 v81, 0xbfb8aa3b, v81
	v_exp_f32_e32 v74, v74
	v_exp_f32_e32 v75, v75
	v_exp_f32_e32 v76, v76
	v_exp_f32_e32 v77, v77
	v_exp_f32_e32 v78, v78
	v_exp_f32_e32 v79, v79
	v_exp_f32_e32 v80, v80
	v_exp_f32_e32 v81, v81
	v_add_f32_e32 v74, 1.0, v74
	v_add_f32_e32 v75, 1.0, v75
	v_add_f32_e32 v76, 1.0, v76
	v_add_f32_e32 v77, 1.0, v77
	v_add_f32_e32 v78, 1.0, v78
	v_add_f32_e32 v79, 1.0, v79
	v_add_f32_e32 v80, 1.0, v80
	v_add_f32_e32 v81, 1.0, v81
	v_rcp_f32_e32 v74, v74
	v_rcp_f32_e32 v75, v75
	v_rcp_f32_e32 v76, v76
	v_rcp_f32_e32 v77, v77
	v_rcp_f32_e32 v78, v78
	v_rcp_f32_e32 v79, v79
	v_rcp_f32_e32 v80, v80
	v_rcp_f32_e32 v81, v81
	s_nop 0
	v_cvt_pk_bf16_f32 v160, v74, v75
	v_cvt_pk_bf16_f32 v161, v76, v77
	v_cvt_pk_bf16_f32 v162, v78, v79
	v_cvt_pk_bf16_f32 v163, v80, v81
	v_mul_f32_e32 v82, 0xbfb8aa3b, v82
	v_mul_f32_e32 v83, 0xbfb8aa3b, v83
	v_mul_f32_e32 v84, 0xbfb8aa3b, v84
	v_mul_f32_e32 v85, 0xbfb8aa3b, v85
	v_mul_f32_e32 v86, 0xbfb8aa3b, v86
	v_mul_f32_e32 v87, 0xbfb8aa3b, v87
	v_mul_f32_e32 v88, 0xbfb8aa3b, v88
	v_mul_f32_e32 v89, 0xbfb8aa3b, v89
	v_exp_f32_e32 v82, v82
	v_exp_f32_e32 v83, v83
	v_exp_f32_e32 v84, v84
	v_exp_f32_e32 v85, v85
	v_exp_f32_e32 v86, v86
	v_exp_f32_e32 v87, v87
	v_exp_f32_e32 v88, v88
	v_exp_f32_e32 v89, v89
	v_add_f32_e32 v82, 1.0, v82
	v_add_f32_e32 v83, 1.0, v83
	v_add_f32_e32 v84, 1.0, v84
	v_add_f32_e32 v85, 1.0, v85
	v_add_f32_e32 v86, 1.0, v86
	v_add_f32_e32 v87, 1.0, v87
	v_add_f32_e32 v88, 1.0, v88
	v_add_f32_e32 v89, 1.0, v89
	v_rcp_f32_e32 v82, v82
	v_rcp_f32_e32 v83, v83
	v_rcp_f32_e32 v84, v84
	v_rcp_f32_e32 v85, v85
	v_rcp_f32_e32 v86, v86
	v_rcp_f32_e32 v87, v87
	v_rcp_f32_e32 v88, v88
	v_rcp_f32_e32 v89, v89
	s_nop 0
	v_cvt_pk_bf16_f32 v164, v82, v83
	v_cvt_pk_bf16_f32 v165, v84, v85
	v_cvt_pk_bf16_f32 v166, v86, v87
	v_cvt_pk_bf16_f32 v167, v88, v89
	v_mul_f32_e32 v90, 0xbfb8aa3b, v90
	v_mul_f32_e32 v91, 0xbfb8aa3b, v91
	v_mul_f32_e32 v92, 0xbfb8aa3b, v92
	v_mul_f32_e32 v93, 0xbfb8aa3b, v93
	v_mul_f32_e32 v94, 0xbfb8aa3b, v94
	v_mul_f32_e32 v95, 0xbfb8aa3b, v95
	v_mul_f32_e32 v96, 0xbfb8aa3b, v96
	v_mul_f32_e32 v97, 0xbfb8aa3b, v97
	v_exp_f32_e32 v90, v90
	v_exp_f32_e32 v91, v91
	v_exp_f32_e32 v92, v92
	v_exp_f32_e32 v93, v93
	v_exp_f32_e32 v94, v94
	v_exp_f32_e32 v95, v95
	v_exp_f32_e32 v96, v96
	v_exp_f32_e32 v97, v97
	v_add_f32_e32 v90, 1.0, v90
	v_add_f32_e32 v91, 1.0, v91
	v_add_f32_e32 v92, 1.0, v92
	v_add_f32_e32 v93, 1.0, v93
	v_add_f32_e32 v94, 1.0, v94
	v_add_f32_e32 v95, 1.0, v95
	v_add_f32_e32 v96, 1.0, v96
	v_add_f32_e32 v97, 1.0, v97
	v_rcp_f32_e32 v90, v90
	v_rcp_f32_e32 v91, v91
	v_rcp_f32_e32 v92, v92
	v_rcp_f32_e32 v93, v93
	v_rcp_f32_e32 v94, v94
	v_rcp_f32_e32 v95, v95
	v_rcp_f32_e32 v96, v96
	v_rcp_f32_e32 v97, v97
	s_nop 0
	v_cvt_pk_bf16_f32 v168, v90, v91
	v_cvt_pk_bf16_f32 v169, v92, v93
	v_cvt_pk_bf16_f32 v170, v94, v95
	v_cvt_pk_bf16_f32 v171, v96, v97
	v_mul_f32_e32 v98, 0xbfb8aa3b, v98
	v_mul_f32_e32 v99, 0xbfb8aa3b, v99
	v_mul_f32_e32 v100, 0xbfb8aa3b, v100
	v_mul_f32_e32 v101, 0xbfb8aa3b, v101
	v_mul_f32_e32 v102, 0xbfb8aa3b, v102
	v_mul_f32_e32 v103, 0xbfb8aa3b, v103
	v_mul_f32_e32 v104, 0xbfb8aa3b, v104
	v_mul_f32_e32 v105, 0xbfb8aa3b, v105
	v_exp_f32_e32 v98, v98
	v_exp_f32_e32 v99, v99
	v_exp_f32_e32 v100, v100
	v_exp_f32_e32 v101, v101
	v_exp_f32_e32 v102, v102
	v_exp_f32_e32 v103, v103
	v_exp_f32_e32 v104, v104
	v_exp_f32_e32 v105, v105
	v_add_f32_e32 v98, 1.0, v98
	v_add_f32_e32 v99, 1.0, v99
	v_add_f32_e32 v100, 1.0, v100
	v_add_f32_e32 v101, 1.0, v101
	v_add_f32_e32 v102, 1.0, v102
	v_add_f32_e32 v103, 1.0, v103
	v_add_f32_e32 v104, 1.0, v104
	v_add_f32_e32 v105, 1.0, v105
	v_rcp_f32_e32 v98, v98
	v_rcp_f32_e32 v99, v99
	v_rcp_f32_e32 v100, v100
	v_rcp_f32_e32 v101, v101
	v_rcp_f32_e32 v102, v102
	v_rcp_f32_e32 v103, v103
	v_rcp_f32_e32 v104, v104
	v_rcp_f32_e32 v105, v105
	s_nop 0
	v_cvt_pk_bf16_f32 v172, v98, v99
	v_cvt_pk_bf16_f32 v173, v100, v101
	v_cvt_pk_bf16_f32 v174, v102, v103
	v_cvt_pk_bf16_f32 v175, v104, v105
	v_mul_f32_e32 v106, 0xbfb8aa3b, v106
	v_mul_f32_e32 v107, 0xbfb8aa3b, v107
	v_mul_f32_e32 v108, 0xbfb8aa3b, v108
	v_mul_f32_e32 v109, 0xbfb8aa3b, v109
	v_mul_f32_e32 v110, 0xbfb8aa3b, v110
	v_mul_f32_e32 v111, 0xbfb8aa3b, v111
	v_mul_f32_e32 v112, 0xbfb8aa3b, v112
	v_mul_f32_e32 v113, 0xbfb8aa3b, v113
; DI unsigned pack2(float a, float b) { f32v2 v = {a, b}; return __builtin_bit_cast(unsigned, __builtin_convertvector(v, bf16v2)); }
; DI float sigm_fast(float x) { return __builtin_amdgcn_rcpf(1.f + __expf(-x)); }
; DI void phase_merge(const Params& p, int l, char* smem, int tid) {
;     ...
; #pragma unroll
;         for (int b2 = 0; b2 < 2; b2++)
; #pragma unroll
;           for (int e = 0; e < 8; e++) sg[b2][e] = pack2(sigm_fast(m[0][b2][2 * e]), sigm_fast(m[0][b2][2 * e + 1]));
;       }
;       f32x16 t[1][2]; zero_acc<1>(t);
;       gemm_main<1>(p.G + (size_t)m0 * 1024 + i * 256, 1024, p.WtBr + ((size_t)l * 4 + i) * 1024 * 256 + (size_t)n0 * 256, 256, 256, t, s, tid);
	v_exp_f32_e32 v106, v106
	v_exp_f32_e32 v107, v107
	v_exp_f32_e32 v108, v108
	v_exp_f32_e32 v109, v109
	v_exp_f32_e32 v110, v110
	v_exp_f32_e32 v111, v111
	v_exp_f32_e32 v112, v112
	v_exp_f32_e32 v113, v113
	v_add_f32_e32 v106, 1.0, v106
	v_add_f32_e32 v107, 1.0, v107
	v_add_f32_e32 v108, 1.0, v108
	v_add_f32_e32 v109, 1.0, v109
	v_add_f32_e32 v110, 1.0, v110
	v_add_f32_e32 v111, 1.0, v111
	v_add_f32_e32 v112, 1.0, v112
	v_add_f32_e32 v113, 1.0, v113
	v_rcp_f32_e32 v106, v106
	v_rcp_f32_e32 v107, v107
	v_rcp_f32_e32 v108, v108
	v_rcp_f32_e32 v109, v109
	v_rcp_f32_e32 v110, v110
	v_rcp_f32_e32 v111, v111
	v_rcp_f32_e32 v112, v112
	v_rcp_f32_e32 v113, v113
	s_nop 0
	v_cvt_pk_bf16_f32 v176, v106, v107
	v_cvt_pk_bf16_f32 v177, v108, v109
	v_cvt_pk_bf16_f32 v178, v110, v111
	v_cvt_pk_bf16_f32 v179, v112, v113
	v_mul_f32_e32 v114, 0xbfb8aa3b, v114
	v_mul_f32_e32 v115, 0xbfb8aa3b, v115
	v_mul_f32_e32 v116, 0xbfb8aa3b, v116
	v_mul_f32_e32 v117, 0xbfb8aa3b, v117
	v_mul_f32_e32 v118, 0xbfb8aa3b, v118
	v_mul_f32_e32 v119, 0xbfb8aa3b, v119
	v_mul_f32_e32 v120, 0xbfb8aa3b, v120
	v_mul_f32_e32 v121, 0xbfb8aa3b, v121
	v_exp_f32_e32 v114, v114
	v_exp_f32_e32 v115, v115
	v_exp_f32_e32 v116, v116
	v_exp_f32_e32 v117, v117
	v_exp_f32_e32 v118, v118
	v_exp_f32_e32 v119, v119
	v_exp_f32_e32 v120, v120
	v_exp_f32_e32 v121, v121
	v_add_f32_e32 v114, 1.0, v114
	v_add_f32_e32 v115, 1.0, v115
	v_add_f32_e32 v116, 1.0, v116
	v_add_f32_e32 v117, 1.0, v117
	v_add_f32_e32 v118, 1.0, v118
	v_add_f32_e32 v119, 1.0, v119
	v_add_f32_e32 v120, 1.0, v120
	v_add_f32_e32 v121, 1.0, v121
	v_rcp_f32_e32 v114, v114
	v_rcp_f32_e32 v115, v115
	v_rcp_f32_e32 v116, v116
	v_rcp_f32_e32 v117, v117
	v_rcp_f32_e32 v118, v118
	v_rcp_f32_e32 v119, v119
	v_rcp_f32_e32 v120, v120
	v_rcp_f32_e32 v121, v121
	s_nop 0
	v_cvt_pk_bf16_f32 v180, v114, v115
	v_cvt_pk_bf16_f32 v181, v116, v117
	v_cvt_pk_bf16_f32 v182, v118, v119
	v_cvt_pk_bf16_f32 v183, v120, v121
	v_mul_f32_e32 v122, 0xbfb8aa3b, v122
	v_mul_f32_e32 v123, 0xbfb8aa3b, v123
	v_mul_f32_e32 v124, 0xbfb8aa3b, v124
	v_mul_f32_e32 v125, 0xbfb8aa3b, v125
	v_mul_f32_e32 v126, 0xbfb8aa3b, v126
	v_mul_f32_e32 v127, 0xbfb8aa3b, v127
	v_mul_f32_e32 v128, 0xbfb8aa3b, v128
	v_mul_f32_e32 v129, 0xbfb8aa3b, v129
	v_exp_f32_e32 v122, v122
	v_exp_f32_e32 v123, v123
	v_exp_f32_e32 v124, v124
	v_exp_f32_e32 v125, v125
	v_exp_f32_e32 v126, v126
	v_exp_f32_e32 v127, v127
	v_exp_f32_e32 v128, v128
	v_exp_f32_e32 v129, v129
	v_add_f32_e32 v122, 1.0, v122
	v_add_f32_e32 v123, 1.0, v123
	v_add_f32_e32 v124, 1.0, v124
	v_add_f32_e32 v125, 1.0, v125
	v_add_f32_e32 v126, 1.0, v126
	v_add_f32_e32 v127, 1.0, v127
	v_add_f32_e32 v128, 1.0, v128
	v_add_f32_e32 v129, 1.0, v129
	v_rcp_f32_e32 v122, v122
	v_rcp_f32_e32 v123, v123
	v_rcp_f32_e32 v124, v124
	v_rcp_f32_e32 v125, v125
	v_rcp_f32_e32 v126, v126
	v_rcp_f32_e32 v127, v127
	v_rcp_f32_e32 v128, v128
	v_rcp_f32_e32 v129, v129
	s_nop 0
	v_cvt_pk_bf16_f32 v184, v122, v123
	v_cvt_pk_bf16_f32 v185, v124, v125
	v_cvt_pk_bf16_f32 v186, v126, v127
	v_cvt_pk_bf16_f32 v187, v128, v129
	s_add_u32 s13, s13, 1
	v_mov_b32_e32 v66, 0
	v_mov_b32_e32 v67, 0
	v_mov_b32_e32 v68, 0
	v_mov_b32_e32 v69, 0
	v_mov_b32_e32 v70, 0
	v_mov_b32_e32 v71, 0
	v_mov_b32_e32 v72, 0
	v_mov_b32_e32 v73, 0
	v_mov_b32_e32 v74, 0
	v_mov_b32_e32 v75, 0
	v_mov_b32_e32 v76, 0
	v_mov_b32_e32 v77, 0
	v_mov_b32_e32 v78, 0
	v_mov_b32_e32 v79, 0
	v_mov_b32_e32 v80, 0
	v_mov_b32_e32 v81, 0
	v_mov_b32_e32 v82, 0
	v_mov_b32_e32 v83, 0
	v_mov_b32_e32 v84, 0
	v_mov_b32_e32 v85, 0
	v_mov_b32_e32 v86, 0
	v_mov_b32_e32 v87, 0
	v_mov_b32_e32 v88, 0
	v_mov_b32_e32 v89, 0
	v_mov_b32_e32 v90, 0
	v_mov_b32_e32 v91, 0
	v_mov_b32_e32 v92, 0
	v_mov_b32_e32 v93, 0
	v_mov_b32_e32 v94, 0
	v_mov_b32_e32 v95, 0
	v_mov_b32_e32 v96, 0
	v_mov_b32_e32 v97, 0
	v_mov_b32_e32 v98, 0
	v_mov_b32_e32 v99, 0
	v_mov_b32_e32 v100, 0
	v_mov_b32_e32 v101, 0
	v_mov_b32_e32 v102, 0
	v_mov_b32_e32 v103, 0
	v_mov_b32_e32 v104, 0
	v_mov_b32_e32 v105, 0
	v_mov_b32_e32 v106, 0
	v_mov_b32_e32 v107, 0
	v_mov_b32_e32 v108, 0
	v_mov_b32_e32 v109, 0
	v_mov_b32_e32 v110, 0
	v_mov_b32_e32 v111, 0
	v_mov_b32_e32 v112, 0
	v_mov_b32_e32 v113, 0
	v_mov_b32_e32 v114, 0
	v_mov_b32_e32 v115, 0
	v_mov_b32_e32 v116, 0
	v_mov_b32_e32 v117, 0
	v_mov_b32_e32 v118, 0
	v_mov_b32_e32 v119, 0
	v_mov_b32_e32 v120, 0
	v_mov_b32_e32 v121, 0
	v_mov_b32_e32 v122, 0
	v_mov_b32_e32 v123, 0
	v_mov_b32_e32 v124, 0
	v_mov_b32_e32 v125, 0
	v_mov_b32_e32 v126, 0
	v_mov_b32_e32 v127, 0
	v_mov_b32_e32 v128, 0
	v_mov_b32_e32 v129, 0
	s_waitcnt vmcnt(0) lgkmcnt(0)
	s_barrier
	ds_read_b128 v[224:227], v138 offset:0
	ds_read_b128 v[232:235], v142 offset:0
	ds_read_b128 v[228:231], v138 offset:4096
	ds_read_b128 v[236:239], v142 offset:4096
	s_add_u32 m0, s10, 0x8000
	s_nop 0
	global_load_lds_dwordx4 v200, s[4:5]
	s_add_u32 m0, s10, 0x8400
	s_nop 0
	global_load_lds_dwordx4 v201, s[4:5]
	s_mov_b32 s11, 1
; #define G_STORE(S, bf) { *(uint4*)&s->a[bf][srow][skc] = S##a0; *(uint4*)&s->a[bf][srow + 32][skc] = S##a1; \
;     if (MB == 2) { *(uint4*)&s->a[bf][srow + 64][skc] = S##a2; *(uint4*)&s->a[bf][srow + 96][skc] = S##a3; } \
;     *(uint4*)&s->b[bf][srow][skc] = S##b0; *(uint4*)&s->b[bf][srow + 32][skc] = S##b1; *(uint4*)&s->b[bf][srow + 64][skc] = S##b2; *(uint4*)&s->b[bf][srow + 96][skc] = S##b3; }
; template <int MB, bool PF2 = true>
; DI void gemm_main(const u16* __restrict__ A, int lda, const u16* __restrict__ B, int ldb, int K, f32x16 (&acc)[MB][2], GemmLds* s, int tid) {
;     ...
;   for (int kt = 0; kt < KT; kt += 2) {
;     { const int k2 = min((kt + 2) * 64, klast); G_LOAD(q, k2); }
;     __builtin_amdgcn_sched_barrier(0);
;     G_COMPUTE(0);
;     G_STORE(p, 1);
;     __syncthreads();
;     { const int k3 = min((kt + 3) * 64, klast); G_LOAD(p, k3); }
;     __builtin_amdgcn_sched_barrier(0);
;     G_COMPUTE(1);
;     G_STORE(q, 0);
;     __syncthreads();
;   }
.Lmgt_loop:
	ds_read_b128 v[240:243], v139 offset:0
	ds_read_b128 v[192:195], v143 offset:0
	ds_read_b128 v[188:191], v139 offset:4096
	ds_read_b128 v[196:199], v143 offset:4096
	s_waitcnt lgkmcnt(4)
	s_add_u32 m0, s10, 0x8800
	v_mfma_f32_32x32x16_bf16 v[66:81], v[232:235], v[224:227], v[66:81]
	global_load_lds_dwordx4 v202, s[4:5]
	s_add_u32 m0, s10, 0x8c00
	v_mfma_f32_32x32x16_bf16 v[82:97], v[236:239], v[224:227], v[82:97]
	global_load_lds_dwordx4 v203, s[4:5]
	s_add_u32 s4, s4, 128
	s_addc_u32 s5, s5, 0
	v_mfma_f32_32x32x16_bf16 v[98:113], v[232:235], v[228:231], v[98:113]
	v_mfma_f32_32x32x16_bf16 v[114:129], v[236:239], v[228:231], v[114:129]
	ds_read_b128 v[224:227], v140 offset:0
	ds_read_b128 v[232:235], v144 offset:0
	ds_read_b128 v[228:231], v140 offset:4096
	ds_read_b128 v[236:239], v144 offset:4096
	s_waitcnt lgkmcnt(4)
	s_add_u32 m0, s10, 0xc000
	v_mfma_f32_32x32x16_bf16 v[66:81], v[192:195], v[240:243], v[66:81]
	global_load_lds_dwordx4 v130, s[8:9]
	s_add_u32 m0, s10, 0xc400
	v_mfma_f32_32x32x16_bf16 v[82:97], v[196:199], v[240:243], v[82:97]
	global_load_lds_dwordx4 v131, s[8:9]
	v_mfma_f32_32x32x16_bf16 v[98:113], v[192:195], v[188:191], v[98:113]
	v_mfma_f32_32x32x16_bf16 v[114:129], v[196:199], v[188:191], v[114:129]
	ds_read_b128 v[240:243], v141 offset:0
	ds_read_b128 v[192:195], v145 offset:0
	ds_read_b128 v[188:191], v141 offset:4096
	ds_read_b128 v[196:199], v145 offset:4096
	s_waitcnt lgkmcnt(4)
	s_add_u32 m0, s10, 0xc800
	v_mfma_f32_32x32x16_bf16 v[66:81], v[232:235], v[224:227], v[66:81]
	global_load_lds_dwordx4 v132, s[8:9]
	s_add_u32 m0, s10, 0xcc00
	v_mfma_f32_32x32x16_bf16 v[82:97], v[236:239], v[224:227], v[82:97]
	global_load_lds_dwordx4 v133, s[8:9]
	s_add_u32 s8, s8, 128
	s_addc_u32 s9, s9, 0
	v_mfma_f32_32x32x16_bf16 v[98:113], v[232:235], v[228:231], v[98:113]
	v_mfma_f32_32x32x16_bf16 v[114:129], v[236:239], v[228:231], v[114:129]
	s_waitcnt vmcnt(0) lgkmcnt(0)
	s_barrier
	ds_read_b128 v[224:227], v138 offset:32768
	ds_read_b128 v[232:235], v142 offset:32768
	ds_read_b128 v[228:231], v138 offset:36864
	ds_read_b128 v[236:239], v142 offset:36864
	s_cmp_eq_u32 s11, 0
	s_cbranch_scc1 .Lmgt_hold0
	s_add_u32 m0, s10, 0x0
	v_mfma_f32_32x32x16_bf16 v[66:81], v[192:195], v[240:243], v[66:81]
	global_load_lds_dwordx4 v200, s[4:5]
	s_add_u32 m0, s10, 0x400
	v_mfma_f32_32x32x16_bf16 v[82:97], v[196:199], v[240:243], v[82:97]
	global_load_lds_dwordx4 v201, s[4:5]
	v_mfma_f32_32x32x16_bf16 v[98:113], v[192:195], v[188:191], v[98:113]
	v_mfma_f32_32x32x16_bf16 v[114:129], v[196:199], v[188:191], v[114:129]
	s_branch .Lmgt_held0

; #define G_STORE(S, bf) { *(uint4*)&s->a[bf][srow][skc] = S##a0; *(uint4*)&s->a[bf][srow + 32][skc] = S##a1; \
;     if (MB == 2) { *(uint4*)&s->a[bf][srow + 64][skc] = S##a2; *(uint4*)&s->a[bf][srow + 96][skc] = S##a3; } \
;     *(uint4*)&s->b[bf][srow][skc] = S##b0; *(uint4*)&s->b[bf][srow + 32][skc] = S##b1; *(uint4*)&s->b[bf][srow + 64][skc] = S##b2; *(uint4*)&s->b[bf][srow + 96][skc] = S##b3; }
; template <int MB, bool PF2 = true>
; DI void gemm_main(const u16* __restrict__ A, int lda, const u16* __restrict__ B, int ldb, int K, f32x16 (&acc)[MB][2], GemmLds* s, int tid) {
;     ...
;   for (int kt = 0; kt < KT; kt += 2) {
;     { const int k2 = min((kt + 2) * 64, klast); G_LOAD(q, k2); }
;     __builtin_amdgcn_sched_barrier(0);
;     G_COMPUTE(0);
;     G_STORE(p, 1);
;     __syncthreads();
;     { const int k3 = min((kt + 3) * 64, klast); G_LOAD(p, k3); }
;     __builtin_amdgcn_sched_barrier(0);
;     G_COMPUTE(1);
;     G_STORE(q, 0);
;     __syncthreads();
;   }
.Lmgt_held0:
	s_cmp_eq_u32 s11, 0
	s_cbranch_scc1 .Lmgt_last
	ds_read_b128 v[240:243], v139 offset:32768
	ds_read_b128 v[192:195], v143 offset:32768
	ds_read_b128 v[188:191], v139 offset:36864
	ds_read_b128 v[196:199], v143 offset:36864
	s_waitcnt lgkmcnt(4)
	s_add_u32 m0, s10, 0x800
	v_mfma_f32_32x32x16_bf16 v[66:81], v[232:235], v[224:227], v[66:81]
	global_load_lds_dwordx4 v202, s[4:5]
	s_add_u32 m0, s10, 0xc00
	v_mfma_f32_32x32x16_bf16 v[82:97], v[236:239], v[224:227], v[82:97]
	global_load_lds_dwordx4 v203, s[4:5]
	s_add_u32 s4, s4, 128
	s_addc_u32 s5, s5, 0
	v_mfma_f32_32x32x16_bf16 v[98:113], v[232:235], v[228:231], v[98:113]
	v_mfma_f32_32x32x16_bf16 v[114:129], v[236:239], v[228:231], v[114:129]
	ds_read_b128 v[224:227], v140 offset:32768
	ds_read_b128 v[232:235], v144 offset:32768
	ds_read_b128 v[228:231], v140 offset:36864
	ds_read_b128 v[236:239], v144 offset:36864
	s_waitcnt lgkmcnt(4)
	s_add_u32 m0, s10, 0x4000
	v_mfma_f32_32x32x16_bf16 v[66:81], v[192:195], v[240:243], v[66:81]
	global_load_lds_dwordx4 v130, s[8:9]
	s_add_u32 m0, s10, 0x4400
	v_mfma_f32_32x32x16_bf16 v[82:97], v[196:199], v[240:243], v[82:97]
	global_load_lds_dwordx4 v131, s[8:9]
	v_mfma_f32_32x32x16_bf16 v[98:113], v[192:195], v[188:191], v[98:113]
	v_mfma_f32_32x32x16_bf16 v[114:129], v[196:199], v[188:191], v[114:129]
	ds_read_b128 v[240:243], v141 offset:32768
	ds_read_b128 v[192:195], v145 offset:32768
	ds_read_b128 v[188:191], v141 offset:36864
	ds_read_b128 v[196:199], v145 offset:36864
	s_waitcnt lgkmcnt(4)
	s_add_u32 m0, s10, 0x4800
	v_mfma_f32_32x32x16_bf16 v[66:81], v[232:235], v[224:227], v[66:81]
	global_load_lds_dwordx4 v132, s[8:9]
	s_add_u32 m0, s10, 0x4c00
	v_mfma_f32_32x32x16_bf16 v[82:97], v[236:239], v[224:227], v[82:97]
	global_load_lds_dwordx4 v133, s[8:9]
	s_add_u32 s8, s8, 128
	s_addc_u32 s9, s9, 0
	v_mfma_f32_32x32x16_bf16 v[98:113], v[232:235], v[228:231], v[98:113]
	v_mfma_f32_32x32x16_bf16 v[114:129], v[236:239], v[228:231], v[114:129]
	s_waitcnt vmcnt(0) lgkmcnt(0)
	s_barrier
	ds_read_b128 v[224:227], v138 offset:0
	ds_read_b128 v[232:235], v142 offset:0
	ds_read_b128 v[228:231], v138 offset:4096
	ds_read_b128 v[236:239], v142 offset:4096
	s_add_u32 m0, s10, 0x8000
	v_mfma_f32_32x32x16_bf16 v[66:81], v[192:195], v[240:243], v[66:81]
	global_load_lds_dwordx4 v200, s[4:5]
	s_add_u32 m0, s10, 0x8400
	v_mfma_f32_32x32x16_bf16 v[82:97], v[196:199], v[240:243], v[82:97]
	global_load_lds_dwordx4 v201, s[4:5]
	v_mfma_f32_32x32x16_bf16 v[98:113], v[192:195], v[188:191], v[98:113]
	v_mfma_f32_32x32x16_bf16 v[114:129], v[196:199], v[188:191], v[114:129]
	s_sub_u32 s11, s11, 1
	s_branch .Lmgt_loop

; DI void phase_outproj(const Params& p, int l, char* smem, int tid) {
;     ...
;   for (int it = (dyn ? fetch_item(qc, smem) : (int)blockIdx.x); it < 272 * 8; it = (dyn ? fetch_item(qc, smem) : it + (int)gridDim.x)) {
;     const int mt = it >> 3, nt = it & 7, m0 = mt * 128, n0 = nt * 128;
;     if (l == 1 && (mt % 34) < 2) continue;
;     f32x16 acc[2][2]; zero_acc<2>(acc);
;     gemm_main<2>(ACC + (size_t)m0 * 1024, 1024, p.WtOut + (size_t)l * 1024 * 1024 + (size_t)n0 * 1024, 1024, 1024, acc, s, tid);
;     u16* O = p.G;
; #pragma unroll
;     for (int mb = 0; mb < 2; mb++)
; #pragma unroll
;       for (int nb = 0; nb < 2; nb++) {
;         const int rowb = m0 + wm * 64 + mb * 32, col = n0 + wn * 64 + nb * 32 + r;
;         const int b = rowb / SEQA, pos0 = rowb % SEQA;
;         const float gate = p.mod[((size_t)l * 9 + ((pos0 < CTXL) ? 8 : b)) * 3072 + 2048 + col];
.Lop_again:
	s_and_b32 s13, s12, 7
	s_mul_i32 s7, s18, 9
	s_add_u32 s7, s7, s21
	s_mul_i32 s7, s7, 0x3000
	s_lshl_b32 s6, s13, 9
	s_add_u32 s7, s7, s6
	s_add_u32 s7, s7, 0x1d002000
	s_add_u32 s6, s96, s7
	s_addc_u32 s7, s97, 0
	global_load_dwordx4 v[116:119], v111, s[6:7] offset:0
	global_load_dwordx4 v[120:123], v111, s[6:7] offset:32
	global_load_dwordx4 v[124:127], v111, s[6:7] offset:64
	global_load_dwordx4 v[128:131], v111, s[6:7] offset:96
	global_load_dwordx4 v[132:135], v111, s[6:7] offset:128
	global_load_dwordx4 v[136:139], v111, s[6:7] offset:160
	global_load_dwordx4 v[140:143], v111, s[6:7] offset:192
	global_load_dwordx4 v[144:147], v111, s[6:7] offset:224
	s_lshl_b32 s2, s20, 18
	s_add_u32 s4, s90, s2
	s_addc_u32 s5, s91, 0
	s_lshl_b32 s3, s13, 18
	s_add_u32 s8, s14, s3
	s_addc_u32 s9, s15, 0
	s_lshl_b32 s3, s13, 8
	s_add_u32 s2, s2, s3
	s_add_u32 s2, s2, 0x16720000
	s_add_u32 s16, s96, s2
	s_addc_u32 s17, s97, 0
	v_mov_b32_e32 v2, 0
	v_mov_b32_e32 v3, 0
	v_mov_b32_e32 v4, 0
	v_mov_b32_e32 v5, 0
	v_mov_b32_e32 v6, 0
	v_mov_b32_e32 v7, 0
	v_mov_b32_e32 v8, 0
	v_mov_b32_e32 v9, 0
	v_mov_b32_e32 v10, 0
	v_mov_b32_e32 v11, 0
	v_mov_b32_e32 v12, 0
	v_mov_b32_e32 v13, 0
	v_mov_b32_e32 v14, 0
	v_mov_b32_e32 v15, 0
	v_mov_b32_e32 v16, 0
	v_mov_b32_e32 v17, 0
	v_mov_b32_e32 v18, 0
	v_mov_b32_e32 v19, 0
	v_mov_b32_e32 v20, 0
	v_mov_b32_e32 v21, 0
	v_mov_b32_e32 v22, 0
	v_mov_b32_e32 v23, 0
	v_mov_b32_e32 v24, 0
	v_mov_b32_e32 v25, 0
	v_mov_b32_e32 v26, 0
	v_mov_b32_e32 v27, 0
	v_mov_b32_e32 v28, 0
	v_mov_b32_e32 v29, 0
	v_mov_b32_e32 v30, 0
	v_mov_b32_e32 v31, 0
	v_mov_b32_e32 v32, 0
	v_mov_b32_e32 v33, 0
	v_mov_b32_e32 v34, 0
	v_mov_b32_e32 v35, 0
	v_mov_b32_e32 v36, 0
	v_mov_b32_e32 v37, 0
	v_mov_b32_e32 v38, 0
	v_mov_b32_e32 v39, 0
	v_mov_b32_e32 v40, 0
	v_mov_b32_e32 v41, 0
	v_mov_b32_e32 v42, 0
	v_mov_b32_e32 v43, 0
	v_mov_b32_e32 v44, 0
	v_mov_b32_e32 v45, 0
	v_mov_b32_e32 v46, 0
	v_mov_b32_e32 v47, 0
	v_mov_b32_e32 v48, 0
	v_mov_b32_e32 v49, 0
	v_mov_b32_e32 v50, 0
	v_mov_b32_e32 v51, 0
	v_mov_b32_e32 v52, 0
	v_mov_b32_e32 v53, 0
	v_mov_b32_e32 v54, 0
	v_mov_b32_e32 v55, 0
	v_mov_b32_e32 v56, 0
	v_mov_b32_e32 v57, 0
	v_mov_b32_e32 v58, 0
	v_mov_b32_e32 v59, 0
	v_mov_b32_e32 v60, 0
	v_mov_b32_e32 v61, 0
	v_mov_b32_e32 v62, 0
	v_mov_b32_e32 v63, 0
	v_mov_b32_e32 v64, 0
	v_mov_b32_e32 v65, 0
	s_add_u32 m0, s10, 0x0
	s_nop 0
	global_load_lds_dwordx4 v98, s[4:5]
	s_add_u32 m0, s10, 0x400
	s_nop 0
	global_load_lds_dwordx4 v99, s[4:5]
	s_add_u32 m0, s10, 0x800
	s_nop 0
	global_load_lds_dwordx4 v100, s[4:5]
	s_add_u32 m0, s10, 0xc00
	s_nop 0
	global_load_lds_dwordx4 v101, s[4:5]
	s_add_u32 m0, s10, 0x4000
	s_nop 0
	global_load_lds_dwordx4 v98, s[8:9]
	s_add_u32 m0, s10, 0x4400
	s_nop 0
	global_load_lds_dwordx4 v99, s[8:9]
	s_add_u32 m0, s10, 0x4800
	s_nop 0
	global_load_lds_dwordx4 v100, s[8:9]
	s_add_u32 m0, s10, 0x4c00
	s_nop 0
	global_load_lds_dwordx4 v101, s[8:9]
	s_add_u32 s4, s4, 128
	s_addc_u32 s5, s5, 0
	s_add_u32 s8, s8, 128
	s_addc_u32 s9, s9, 0
	s_waitcnt vmcnt(0) lgkmcnt(0)
	s_barrier
	ds_read_b128 v[66:69], v102 offset:0
	ds_read_b128 v[74:77], v106 offset:0
	ds_read_b128 v[70:73], v102 offset:4096
	ds_read_b128 v[78:81], v106 offset:4096
	s_add_u32 m0, s10, 0x8000
	s_nop 0
	global_load_lds_dwordx4 v98, s[4:5]
	s_add_u32 m0, s10, 0x8400
	s_nop 0
	global_load_lds_dwordx4 v99, s[4:5]
	s_mov_b32 s11, 7
